# leading-half epilogue priority held through its next-unit first load segment (reset after first K barrier)
# speedup vs baseline: 1.0020x; 1.0002x over previous
.LBB0_381:
.LBB0_383:
	s_add_u32 s39, s82, 0x100
	s_addc_u32 s67, s83, 0
	s_mov_b32 s94, -2
	s_mov_b64 vcc, 0
	v_lshl_add_u64 v[132:133], s[4:5], 0, v[168:169]
	ds_read_b128 v[134:137], v199
	ds_read_b128 v[138:141], v200
	ds_read_b128 v[142:145], v201
	ds_read_b128 v[146:149], v202
	ds_read_b128 v[150:153], v203
	ds_read_b128 v[174:177], v204
	ds_read_b128 v[178:181], v205
	ds_read_b128 v[182:185], v206
	s_add_u32 s24, s4, vcc_lo
	s_addc_u32 s25, s5, vcc_hi
	s_add_u32 s24, s24, 0x100
	s_addc_u32 s25, s25, 0
	s_add_u32 s82, s39, vcc_lo
	s_addc_u32 s83, s67, vcc_hi
	s_cmpk_eq_i32 vcc_lo, 0x700
	s_cselect_b32 s87, s29, s83
	s_cselect_b32 s86, s38, s82
	s_cselect_b32 s83, s34, s25
	s_cselect_b32 s82, s35, s24
	v_lshl_add_u64 v[154:155], v[132:133], 0, vcc
	v_lshl_add_u64 v[250:251], v[154:155], 0, s[48:49]
	s_add_i32 m0, s79, 0x8000
	s_mov_b64 s[24:25], 0x20080
	ds_read_b128 v[218:221], v207
	ds_read_b128 v[222:225], v207 offset:2048
	ds_read_b128 v[226:229], v208
	ds_read_b128 v[230:233], v208 offset:2048
	ds_read_b128 v[234:237], v207 offset:4096
	ds_read_b128 v[238:241], v207 offset:6144
	ds_read_b128 v[242:245], v208 offset:4096
	ds_read_b128 v[246:249], v208 offset:6144
	global_load_lds_dwordx4 v[250:251], off
	v_lshl_add_u64 v[250:251], v[154:155], 0, s[24:25]
	s_add_i32 m0, s79, 0xa000
	s_mov_b64 s[24:25], 0x60080
	global_load_lds_dwordx4 v[250:251], off
	v_lshl_add_u64 v[250:251], v[154:155], 0, s[50:51]
	s_add_i32 m0, s79, 0xc000
	v_lshl_add_u64 v[154:155], v[154:155], 0, s[24:25]
	global_load_lds_dwordx4 v[250:251], off
	s_add_i32 m0, s79, 0xe000
	s_nop 0
	global_load_lds_dwordx4 v[154:155], off
	s_waitcnt vmcnt(16)
	s_waitcnt lgkmcnt(0)
	s_barrier
	s_setprio 0
	s_cmp_lg_u32 s98, 0
	s_cbranch_scc1 .Lp1b_skip
	v_mbcnt_lo_u32_b32 v255, -1, 0
	v_mbcnt_hi_u32_b32 v255, -1, v255
	s_cmp_gt_i32 s96, 13
	s_cbranch_scc1 .Lp1b_gate
	s_lshl_b32 s100, s96, 10
	s_add_u32 s100, s90, s100
	s_addc_u32 s101, s91, 0
	v_lshlrev_b32_e32 v255, 4, v255
	s_branch .Lp1b_issue

.LBB0_1134:
	s_ashr_i32 s57, s56, 31
	s_lshl_b64 s[60:61], s[56:57], 19
	s_add_u32 s60, s42, s60
	s_addc_u32 s61, s43, s61
	s_and_b64 s[62:63], s[10:11], exec
	s_cselect_b32 s57, s61, s27
	s_cselect_b32 s79, s60, s26
	s_ashr_i32 s59, s58, 31
	s_lshl_b64 s[62:63], s[58:59], 19
	v_readlane_b32 s70, v254, 7
	v_readlane_b32 s71, v254, 8
	s_add_u32 s62, s70, s62
	s_addc_u32 s63, s71, s63
	s_and_b64 s[70:71], s[10:11], exec
	s_cselect_b32 s59, s63, s69
	s_cselect_b32 s80, s62, s68
	s_add_u32 s81, s68, 0x100
	v_lshl_add_u64 v[138:139], s[26:27], 0, v[132:133]
	s_addc_u32 s82, s69, 0
	s_mov_b32 s83, -2
	s_mov_b64 s[68:69], 0
	ds_read_b128 v[168:171], v145
	ds_read_b128 v[174:177], v146
	ds_read_b128 v[178:181], v147
	ds_read_b128 v[182:185], v148
	ds_read_b128 v[194:197], v149
	ds_read_b128 v[198:201], v150
	ds_read_b128 v[202:205], v151
	ds_read_b128 v[206:209], v152
	s_add_u32 s70, s26, s68
	s_addc_u32 s71, s27, s69
	s_add_u32 s70, s70, 0x100
	s_addc_u32 s71, s71, 0
	s_add_u32 s84, s81, s68
	s_addc_u32 s85, s82, s69
	s_cmpk_eq_i32 s68, 0x700
	s_cselect_b32 s85, s59, s85
	s_cselect_b32 s84, s80, s84
	s_cselect_b32 s71, s57, s71
	s_cselect_b32 s70, s79, s70
	v_lshl_add_u64 v[140:141], v[138:139], 0, s[68:69]
	v_lshl_add_u64 v[242:243], v[140:141], 0, s[22:23]
	s_add_i32 m0, s34, 0x8000
	s_mov_b64 s[86:87], 0x20080
	ds_read_b128 v[210:213], v153
	ds_read_b128 v[214:217], v153 offset:2048
	ds_read_b128 v[218:221], v154
	ds_read_b128 v[222:225], v154 offset:2048
	ds_read_b128 v[226:229], v153 offset:4096
	ds_read_b128 v[230:233], v153 offset:6144
	ds_read_b128 v[234:237], v154 offset:4096
	ds_read_b128 v[238:241], v154 offset:6144
	global_load_lds_dwordx4 v[242:243], off
	v_lshl_add_u64 v[242:243], v[140:141], 0, s[86:87]
	s_add_i32 m0, s34, 0xa000
	s_mov_b64 s[86:87], 0x60080
	global_load_lds_dwordx4 v[242:243], off
	v_lshl_add_u64 v[242:243], v[140:141], 0, s[24:25]
	s_add_i32 m0, s34, 0xc000
	v_lshl_add_u64 v[140:141], v[140:141], 0, s[86:87]
	global_load_lds_dwordx4 v[242:243], off
	s_add_i32 m0, s34, 0xe000
	s_nop 0
	global_load_lds_dwordx4 v[140:141], off
	s_waitcnt lgkmcnt(0)
	s_barrier
	s_setprio 0
	v_mfma_f32_16x16x32_bf16 v[128:131], v[168:171], v[210:213], 0
	v_mfma_f32_16x16x32_bf16 v[128:131], v[174:177], v[218:221], v[128:131]
	v_mfma_f32_16x16x32_bf16 v[112:115], v[168:171], v[214:217], 0
	v_mfma_f32_16x16x32_bf16 v[112:115], v[174:177], v[222:225], v[112:115]
	v_mfma_f32_16x16x32_bf16 v[96:99], v[168:171], v[226:229], 0
	v_mfma_f32_16x16x32_bf16 v[96:99], v[174:177], v[234:237], v[96:99]
	v_mfma_f32_16x16x32_bf16 v[80:83], v[168:171], v[230:233], 0
	v_mfma_f32_16x16x32_bf16 v[80:83], v[174:177], v[238:241], v[80:83]
	v_mfma_f32_16x16x32_bf16 v[76:79], v[178:181], v[230:233], 0
	v_mfma_f32_16x16x32_bf16 v[76:79], v[182:185], v[238:241], v[76:79]
	v_mfma_f32_16x16x32_bf16 v[92:95], v[178:181], v[226:229], 0
	v_mfma_f32_16x16x32_bf16 v[92:95], v[182:185], v[234:237], v[92:95]
	v_mfma_f32_16x16x32_bf16 v[108:111], v[178:181], v[214:217], 0
	v_mfma_f32_16x16x32_bf16 v[108:111], v[182:185], v[222:225], v[108:111]
	v_mfma_f32_16x16x32_bf16 v[124:127], v[178:181], v[210:213], 0
	v_mfma_f32_16x16x32_bf16 v[124:127], v[182:185], v[218:221], v[124:127]
	v_mfma_f32_16x16x32_bf16 v[120:123], v[194:197], v[210:213], 0
	v_mfma_f32_16x16x32_bf16 v[120:123], v[198:201], v[218:221], v[120:123]
	v_mfma_f32_16x16x32_bf16 v[104:107], v[194:197], v[214:217], 0
	v_mfma_f32_16x16x32_bf16 v[104:107], v[198:201], v[222:225], v[104:107]
	v_mfma_f32_16x16x32_bf16 v[88:91], v[194:197], v[226:229], 0
	v_mfma_f32_16x16x32_bf16 v[88:91], v[198:201], v[234:237], v[88:91]
	v_mfma_f32_16x16x32_bf16 v[72:75], v[194:197], v[230:233], 0
	v_mfma_f32_16x16x32_bf16 v[72:75], v[198:201], v[238:241], v[72:75]
	v_mfma_f32_16x16x32_bf16 v[68:71], v[202:205], v[230:233], 0
	v_mfma_f32_16x16x32_bf16 v[68:71], v[206:209], v[238:241], v[68:71]
	v_mfma_f32_16x16x32_bf16 v[84:87], v[202:205], v[226:229], 0
	v_mfma_f32_16x16x32_bf16 v[84:87], v[206:209], v[234:237], v[84:87]
	v_mfma_f32_16x16x32_bf16 v[100:103], v[202:205], v[214:217], 0
	v_mfma_f32_16x16x32_bf16 v[100:103], v[206:209], v[222:225], v[100:103]
	v_mfma_f32_16x16x32_bf16 v[116:119], v[202:205], v[210:213], 0
	v_mfma_f32_16x16x32_bf16 v[116:119], v[206:209], v[218:221], v[116:119]
	s_barrier
	v_lshl_add_u64 v[140:141], s[84:85], 0, v[158:159]
	s_add_i32 s84, s67, s3
	s_mov_b32 m0, s84
	ds_read_b128 v[210:213], v153 offset:16384
	ds_read_b128 v[214:217], v153 offset:18432
	ds_read_b128 v[218:221], v154 offset:16384
	ds_read_b128 v[222:225], v154 offset:18432
	ds_read_b128 v[226:229], v153 offset:20480
	ds_read_b128 v[230:233], v153 offset:22528
	ds_read_b128 v[234:237], v154 offset:20480
	ds_read_b128 v[238:241], v154 offset:22528
	global_load_lds_dwordx4 v[140:141], off
	v_lshl_add_u64 v[242:243], v[140:141], 0, s[0:1]
	s_add_i32 m0, s84, 0x2000
	s_add_i32 s84, s72, s3
	global_load_lds_dwordx4 v[242:243], off
	v_lshl_add_u64 v[242:243], v[140:141], 0, s[12:13]
	s_mov_b32 m0, s84
	s_nop 0
	global_load_lds_dwordx4 v[242:243], off
	v_lshl_add_u64 v[242:243], v[140:141], 0, s[14:15]
	s_add_i32 m0, s84, 0x2000
	s_nop 0
	global_load_lds_dwordx4 v[242:243], off
	s_waitcnt vmcnt(4)
	s_waitcnt lgkmcnt(0)
	s_barrier
	v_mfma_f32_16x16x32_bf16 v[64:67], v[168:171], v[210:213], 0
	v_mfma_f32_16x16x32_bf16 v[64:67], v[174:177], v[218:221], v[64:67]
	v_mfma_f32_16x16x32_bf16 v[48:51], v[168:171], v[214:217], 0
	v_mfma_f32_16x16x32_bf16 v[48:51], v[174:177], v[222:225], v[48:51]
	v_mfma_f32_16x16x32_bf16 v[32:35], v[168:171], v[226:229], 0
	v_mfma_f32_16x16x32_bf16 v[32:35], v[174:177], v[234:237], v[32:35]
	v_mfma_f32_16x16x32_bf16 v[16:19], v[168:171], v[230:233], 0
	v_mfma_f32_16x16x32_bf16 v[16:19], v[174:177], v[238:241], v[16:19]
	v_mfma_f32_16x16x32_bf16 v[12:15], v[178:181], v[230:233], 0
	v_mfma_f32_16x16x32_bf16 v[12:15], v[182:185], v[238:241], v[12:15]
	v_mfma_f32_16x16x32_bf16 v[28:31], v[178:181], v[226:229], 0
	v_mfma_f32_16x16x32_bf16 v[28:31], v[182:185], v[234:237], v[28:31]
	v_mfma_f32_16x16x32_bf16 v[44:47], v[178:181], v[214:217], 0
	v_mfma_f32_16x16x32_bf16 v[44:47], v[182:185], v[222:225], v[44:47]
	v_mfma_f32_16x16x32_bf16 v[60:63], v[178:181], v[210:213], 0
	v_mfma_f32_16x16x32_bf16 v[60:63], v[182:185], v[218:221], v[60:63]
	v_mfma_f32_16x16x32_bf16 v[56:59], v[194:197], v[210:213], 0
	v_mfma_f32_16x16x32_bf16 v[56:59], v[198:201], v[218:221], v[56:59]
	v_mfma_f32_16x16x32_bf16 v[40:43], v[194:197], v[214:217], 0
	v_mfma_f32_16x16x32_bf16 v[40:43], v[198:201], v[222:225], v[40:43]
	v_mfma_f32_16x16x32_bf16 v[24:27], v[194:197], v[226:229], 0
	v_mfma_f32_16x16x32_bf16 v[24:27], v[198:201], v[234:237], v[24:27]
	v_mfma_f32_16x16x32_bf16 v[8:11], v[194:197], v[230:233], 0
	v_mfma_f32_16x16x32_bf16 v[8:11], v[198:201], v[238:241], v[8:11]
	v_mfma_f32_16x16x32_bf16 v[4:7], v[202:205], v[230:233], 0
	v_mfma_f32_16x16x32_bf16 v[4:7], v[206:209], v[238:241], v[4:7]
	v_mfma_f32_16x16x32_bf16 v[20:23], v[202:205], v[226:229], 0
	v_mfma_f32_16x16x32_bf16 v[20:23], v[206:209], v[234:237], v[20:23]
	v_mfma_f32_16x16x32_bf16 v[36:39], v[202:205], v[214:217], 0
	v_mfma_f32_16x16x32_bf16 v[36:39], v[206:209], v[222:225], v[36:39]
	v_mfma_f32_16x16x32_bf16 v[52:55], v[202:205], v[210:213], 0
	v_mfma_f32_16x16x32_bf16 v[52:55], v[206:209], v[218:221], v[52:55]
	s_barrier
	ds_read_b128 v[168:171], v163
	ds_read_b128 v[174:177], v164
	ds_read_b128 v[178:181], v155
	ds_read_b128 v[182:185], v160
	ds_read_b128 v[194:197], v165
	ds_read_b128 v[198:201], v166
	ds_read_b128 v[202:205], v161
	ds_read_b128 v[206:209], v162
	s_mov_b32 m0, s34
	v_lshl_add_u64 v[242:243], s[70:71], 0, v[0:1]
	ds_read_b128 v[210:213], v153 offset:32768
	ds_read_b128 v[214:217], v153 offset:34816
	ds_read_b128 v[218:221], v154 offset:32768
	ds_read_b128 v[222:225], v154 offset:34816
	ds_read_b128 v[226:229], v153 offset:36864
	ds_read_b128 v[230:233], v153 offset:38912
	ds_read_b128 v[234:237], v154 offset:36864
	ds_read_b128 v[238:241], v154 offset:38912
	global_load_lds_dwordx4 v[242:243], off
	v_lshl_add_u64 v[244:245], v[242:243], 0, s[16:17]
	s_mov_b32 m0, s35
	s_nop 0
	global_load_lds_dwordx4 v[244:245], off
	v_lshl_add_u64 v[244:245], v[242:243], 0, s[0:1]
	s_mov_b32 m0, s38
	v_lshl_add_u64 v[242:243], v[242:243], 0, s[18:19]
	global_load_lds_dwordx4 v[244:245], off
	s_mov_b32 m0, s39
	s_nop 0
	global_load_lds_dwordx4 v[242:243], off
	s_waitcnt vmcnt(8)
	s_waitcnt lgkmcnt(0)
	s_barrier
	v_mfma_f32_16x16x32_bf16 v[128:131], v[168:171], v[210:213], v[128:131]
	v_mfma_f32_16x16x32_bf16 v[128:131], v[174:177], v[218:221], v[128:131]
	v_mfma_f32_16x16x32_bf16 v[112:115], v[174:177], v[222:225], v[112:115]
	v_mfma_f32_16x16x32_bf16 v[112:115], v[168:171], v[214:217], v[112:115]
	v_mfma_f32_16x16x32_bf16 v[96:99], v[168:171], v[226:229], v[96:99]
	v_mfma_f32_16x16x32_bf16 v[96:99], v[174:177], v[234:237], v[96:99]
	v_mfma_f32_16x16x32_bf16 v[80:83], v[174:177], v[238:241], v[80:83]
	v_mfma_f32_16x16x32_bf16 v[80:83], v[168:171], v[230:233], v[80:83]
	v_mfma_f32_16x16x32_bf16 v[76:79], v[178:181], v[230:233], v[76:79]
	v_mfma_f32_16x16x32_bf16 v[76:79], v[182:185], v[238:241], v[76:79]
	v_mfma_f32_16x16x32_bf16 v[92:95], v[182:185], v[234:237], v[92:95]
	v_mfma_f32_16x16x32_bf16 v[92:95], v[178:181], v[226:229], v[92:95]
	v_mfma_f32_16x16x32_bf16 v[108:111], v[178:181], v[214:217], v[108:111]
	v_mfma_f32_16x16x32_bf16 v[108:111], v[182:185], v[222:225], v[108:111]
	v_mfma_f32_16x16x32_bf16 v[124:127], v[182:185], v[218:221], v[124:127]
	v_mfma_f32_16x16x32_bf16 v[124:127], v[178:181], v[210:213], v[124:127]
	v_mfma_f32_16x16x32_bf16 v[120:123], v[194:197], v[210:213], v[120:123]
	v_mfma_f32_16x16x32_bf16 v[120:123], v[198:201], v[218:221], v[120:123]
	v_mfma_f32_16x16x32_bf16 v[104:107], v[198:201], v[222:225], v[104:107]
	v_mfma_f32_16x16x32_bf16 v[104:107], v[194:197], v[214:217], v[104:107]
	v_mfma_f32_16x16x32_bf16 v[88:91], v[194:197], v[226:229], v[88:91]
	v_mfma_f32_16x16x32_bf16 v[88:91], v[198:201], v[234:237], v[88:91]
	v_mfma_f32_16x16x32_bf16 v[72:75], v[198:201], v[238:241], v[72:75]
	v_mfma_f32_16x16x32_bf16 v[72:75], v[194:197], v[230:233], v[72:75]
	v_mfma_f32_16x16x32_bf16 v[68:71], v[202:205], v[230:233], v[68:71]
	v_mfma_f32_16x16x32_bf16 v[68:71], v[206:209], v[238:241], v[68:71]
	v_mfma_f32_16x16x32_bf16 v[84:87], v[206:209], v[234:237], v[84:87]
	v_mfma_f32_16x16x32_bf16 v[84:87], v[202:205], v[226:229], v[84:87]
	v_mfma_f32_16x16x32_bf16 v[100:103], v[202:205], v[214:217], v[100:103]
	v_mfma_f32_16x16x32_bf16 v[100:103], v[206:209], v[222:225], v[100:103]
	v_mfma_f32_16x16x32_bf16 v[116:119], v[206:209], v[218:221], v[116:119]
	v_mfma_f32_16x16x32_bf16 v[116:119], v[202:205], v[210:213], v[116:119]
	s_barrier
	s_add_i32 s70, s73, s3
	v_lshl_add_u64 v[242:243], v[140:141], 0, s[22:23]
	s_mov_b32 m0, s70
	ds_read_b128 v[210:213], v153 offset:49152
	ds_read_b128 v[214:217], v153 offset:51200
	ds_read_b128 v[218:221], v154 offset:49152
	ds_read_b128 v[222:225], v154 offset:51200
	ds_read_b128 v[226:229], v153 offset:53248
	ds_read_b128 v[230:233], v153 offset:55296
	ds_read_b128 v[234:237], v154 offset:53248
	ds_read_b128 v[238:241], v154 offset:55296
	global_load_lds_dwordx4 v[242:243], off
	v_lshl_add_u64 v[242:243], v[140:141], 0, s[24:25]
	s_add_i32 m0, s70, 0x2000
	s_add_i32 s70, s77, s3
	global_load_lds_dwordx4 v[242:243], off
	v_lshl_add_u64 v[242:243], v[140:141], 0, s[28:29]
	s_mov_b32 m0, s70
	v_lshl_add_u64 v[140:141], v[140:141], 0, s[36:37]
	global_load_lds_dwordx4 v[242:243], off
	s_add_i32 m0, s70, 0x2000
	s_nop 0
	global_load_lds_dwordx4 v[140:141], off
	s_waitcnt vmcnt(4)
	s_waitcnt lgkmcnt(0)
	s_barrier
	v_mfma_f32_16x16x32_bf16 v[64:67], v[168:171], v[210:213], v[64:67]
	v_mfma_f32_16x16x32_bf16 v[64:67], v[174:177], v[218:221], v[64:67]
	v_mfma_f32_16x16x32_bf16 v[48:51], v[174:177], v[222:225], v[48:51]
	v_mfma_f32_16x16x32_bf16 v[48:51], v[168:171], v[214:217], v[48:51]
	v_mfma_f32_16x16x32_bf16 v[32:35], v[168:171], v[226:229], v[32:35]
	v_mfma_f32_16x16x32_bf16 v[32:35], v[174:177], v[234:237], v[32:35]
	v_mfma_f32_16x16x32_bf16 v[16:19], v[174:177], v[238:241], v[16:19]
	v_mfma_f32_16x16x32_bf16 v[16:19], v[168:171], v[230:233], v[16:19]
	v_mfma_f32_16x16x32_bf16 v[12:15], v[178:181], v[230:233], v[12:15]
	v_mfma_f32_16x16x32_bf16 v[12:15], v[182:185], v[238:241], v[12:15]
	v_mfma_f32_16x16x32_bf16 v[28:31], v[182:185], v[234:237], v[28:31]
	v_mfma_f32_16x16x32_bf16 v[28:31], v[178:181], v[226:229], v[28:31]
	v_mfma_f32_16x16x32_bf16 v[44:47], v[178:181], v[214:217], v[44:47]
	v_mfma_f32_16x16x32_bf16 v[44:47], v[182:185], v[222:225], v[44:47]
	v_mfma_f32_16x16x32_bf16 v[60:63], v[182:185], v[218:221], v[60:63]
	v_mfma_f32_16x16x32_bf16 v[60:63], v[178:181], v[210:213], v[60:63]
	v_mfma_f32_16x16x32_bf16 v[56:59], v[194:197], v[210:213], v[56:59]
	v_mfma_f32_16x16x32_bf16 v[56:59], v[198:201], v[218:221], v[56:59]
	v_mfma_f32_16x16x32_bf16 v[40:43], v[198:201], v[222:225], v[40:43]
	v_mfma_f32_16x16x32_bf16 v[40:43], v[194:197], v[214:217], v[40:43]
	v_mfma_f32_16x16x32_bf16 v[24:27], v[194:197], v[226:229], v[24:27]
	v_mfma_f32_16x16x32_bf16 v[24:27], v[198:201], v[234:237], v[24:27]
	v_mfma_f32_16x16x32_bf16 v[8:11], v[198:201], v[238:241], v[8:11]
	v_mfma_f32_16x16x32_bf16 v[8:11], v[194:197], v[230:233], v[8:11]
	v_mfma_f32_16x16x32_bf16 v[4:7], v[202:205], v[230:233], v[4:7]
	v_mfma_f32_16x16x32_bf16 v[4:7], v[206:209], v[238:241], v[4:7]
	v_mfma_f32_16x16x32_bf16 v[20:23], v[206:209], v[234:237], v[20:23]
	v_mfma_f32_16x16x32_bf16 v[20:23], v[202:205], v[226:229], v[20:23]
	v_mfma_f32_16x16x32_bf16 v[36:39], v[202:205], v[214:217], v[36:39]
	v_mfma_f32_16x16x32_bf16 v[36:39], v[206:209], v[222:225], v[36:39]
	v_mfma_f32_16x16x32_bf16 v[52:55], v[206:209], v[218:221], v[52:55]
	v_mfma_f32_16x16x32_bf16 v[52:55], v[202:205], v[210:213], v[52:55]
	s_barrier
	s_add_i32 s83, s83, 2
	s_add_u32 s68, s68, 0x100
	s_addc_u32 s69, s69, 0
	s_cmp_gt_u32 s83, 13
